# attention pipelined tiles: row-sum accumulation split over two accumulators so no packed add directly follows the packed add it depends on
# speedup vs baseline: 1.0046x; 1.0046x over previous
; template <int BR>
; DI void attn_branch(const AttnCtx& c, unsigned long long tmask, const bf16_t* kbase, size_t kpitch, const bf16_t* vbase, size_t vpitch, f32x16 (&o)[2], float& lsum) {
;     ...
;                 f32x16 s0, s1;
; #pragma unroll
;                 for (int i = 0; i < 16; ++i) { s0[i] = sbias; s1[i] = sbias; }
; #pragma unroll
;                 for (int st = 0; st < 4; ++st) {
;                     const bf16x8 kf0 = *(const LAS bf16x8*)(Ks + c.qi * 72 + 16 * st + 8 * c.hi), kf1 = *(const LAS bf16x8*)(Ks + (32 + c.qi) * 72 + 16 * st + 8 * c.hi);
;                     s0 = MFMA32(kf0, c.q[st], s0); s1 = MFMA32(kf1, c.q[st], s1);
;                 }
;                 float p0[16], p1[16];
; #pragma unroll
;                 for (int i = 0; i < 16; ++i) { p0[i] = __builtin_amdgcn_exp2f(s0[i]); p1[i] = __builtin_amdgcn_exp2f(s1[i]); }
;                 {
;                     float l0 = 0.f, l1 = 0.f;
; #pragma unroll
;                     for (int i = 0; i < 16; ++i) { l0 += p0[i]; l1 += p1[i]; }
;                     lsum += l0 + l1;
;                 }
;                 if (BR == 1) {
; #pragma unroll
;                     for (int gq = 0; gq < 4; ++gq) {
;                         const int jj = jc * 16 + gq * 2 + c.hi;
;                         __hip_atomic_fetch_add(c.impw + jj, (p0[4 * gq] + p0[4 * gq + 1]) + (p0[4 * gq + 2] + p0[4 * gq + 3]), __ATOMIC_RELAXED, __HIP_MEMORY_SCOPE_WORKGROUP);
;                         __hip_atomic_fetch_add(c.impw + jj + 1, p0[4 * gq + 3], __ATOMIC_RELAXED, __HIP_MEMORY_SCOPE_WORKGROUP);
;                     }
; #pragma unroll
;                     for (int gq = 0; gq < 4; ++gq) {
;                         const int jj = jc * 16 + 8 + gq * 2 + c.hi;
;                         __hip_atomic_fetch_add(c.impw + jj, (p1[4 * gq] + p1[4 * gq + 1]) + (p1[4 * gq + 2] + p1[4 * gq + 3]), __ATOMIC_RELAXED, __HIP_MEMORY_SCOPE_WORKGROUP);
;                         if (jj + 1 < 64) __hip_atomic_fetch_add(c.impw + jj + 1, p1[4 * gq + 3], __ATOMIC_RELAXED, __HIP_MEMORY_SCOPE_WORKGROUP);
;                     }
;                 }
;                 if (BR != 0) {
;                     unsigned pa[8], pb[8];
; #pragma unroll
;                     for (int i = 0; i < 8; ++i) { pa[i] = pk2(p0[2 * i], p0[2 * i + 1]); pb[i] = pk2(p1[2 * i], p1[2 * i + 1]); }
; #pragma unroll
;                     for (int f = 0; f < 2; ++f) {
.LBB0_377:
	s_waitcnt lgkmcnt(0)
	s_barrier
	v_lshrrev_b64 v[64:65], s10, v[106:107]
	v_and_b32_e32 v64, 1, v64
	v_cmp_eq_u32_e64 s[0:1], 1, v64
	v_cmp_ne_u32_e32 vcc, 0, v64
	s_cbranch_vccz .LBB0_387
	s_lshl_b32 s15, s10, 6
	v_cndmask_b32_e64 v64, v193, 0, s[0:1]
	s_or_b32 s0, s15, 63
	v_cmp_le_i32_e32 vcc, s0, v171
	s_and_saveexec_b64 s[0:1], vcc
	s_xor_b64 s[0:1], exec, s[0:1]
	s_cbranch_execz .LBB0_380
	v_lshlrev_b32_e32 v80, 1, v170
	v_add3_u32 v109, s14, v185, v80
	ds_read_b128 v[212:215], v109
	ds_read_b128 v[216:219], v109 offset:4608
	ds_read_b128 v[220:223], v109 offset:32
	ds_read_b128 v[224:227], v109 offset:4640
	ds_read_b128 v[228:231], v109 offset:64
	ds_read_b128 v[232:235], v109 offset:4672
	ds_read_b128 v[236:239], v109 offset:96
	ds_read_b128 v[240:243], v109 offset:4704
	v_mov_b32_e32 v65, v64
	v_mov_b32_e32 v66, v64
	v_mov_b32_e32 v67, v64
	v_mov_b32_e32 v68, v64
	v_mov_b32_e32 v69, v64
	v_mov_b32_e32 v70, v64
	v_mov_b32_e32 v71, v64
	v_mov_b32_e32 v72, v64
	v_mov_b32_e32 v73, v64
	v_mov_b32_e32 v74, v64
	v_mov_b32_e32 v75, v64
	v_mov_b32_e32 v76, v64
	v_mov_b32_e32 v77, v64
	v_mov_b32_e32 v78, v64
	v_mov_b32_e32 v79, v64
	s_nop 0
	s_waitcnt lgkmcnt(7)
	v_mfma_f32_32x32x16_bf16 v[80:95], v[212:215], v[130:133], v[64:79]
	s_waitcnt lgkmcnt(5)
	v_mfma_f32_32x32x16_bf16 v[80:95], v[220:223], v[134:137], v[80:95]
	s_waitcnt lgkmcnt(3)
	v_mfma_f32_32x32x16_bf16 v[80:95], v[228:231], v[138:141], v[80:95]
	s_waitcnt lgkmcnt(1)
	v_mfma_f32_32x32x16_bf16 v[80:95], v[236:239], v[142:145], v[80:95]
	s_waitcnt lgkmcnt(0)
	v_mfma_f32_32x32x16_bf16 v[64:79], v[216:219], v[130:133], v[64:79]
	v_mfma_f32_32x32x16_bf16 v[64:79], v[224:227], v[134:137], v[64:79]
	s_nop 9
	v_exp_f32_e32 v80, v80
	v_exp_f32_e32 v81, v81
	v_exp_f32_e32 v82, v82
	v_mfma_f32_32x32x16_bf16 v[64:79], v[232:235], v[138:141], v[64:79]
	v_exp_f32_e32 v83, v83
	v_exp_f32_e32 v84, v84
	v_exp_f32_e32 v85, v85
	v_mfma_f32_32x32x16_bf16 v[64:79], v[240:243], v[142:145], v[64:79]
	v_add3_u32 v251, s14, v186, v170
	v_add_u32_e32 v255, 0x2000, v251
	v_add_u32_e32 v251, 0x3000, v251
	ds_read2_b64 v[212:215], v255 offset0:128 offset1:130
	ds_read2_b64 v[216:219], v251 offset0:160 offset1:162
	ds_read2_b64 v[220:223], v255 offset0:132 offset1:134
	ds_read2_b64 v[224:227], v251 offset0:164 offset1:166
	ds_read2_b64 v[228:231], v255 offset0:136 offset1:138
	ds_read2_b64 v[232:235], v251 offset0:168 offset1:170
	ds_read2_b64 v[236:239], v255 offset0:140 offset1:142
	ds_read2_b64 v[240:243], v251 offset0:172 offset1:174
	v_exp_f32_e32 v86, v86
	v_exp_f32_e32 v87, v87
	v_exp_f32_e32 v88, v88
	v_exp_f32_e32 v89, v89
	v_exp_f32_e32 v90, v90
	v_exp_f32_e32 v91, v91
	v_exp_f32_e32 v92, v92
	v_exp_f32_e32 v93, v93
	v_exp_f32_e32 v94, v94
	v_exp_f32_e32 v95, v95
	v_pk_add_f32 v[252:253], v[80:81], v[82:83]
	v_pk_add_f32 v[254:255], v[84:85], v[86:87]
	v_pk_add_f32 v[252:253], v[88:89], v[252:253]
	v_pk_add_f32 v[254:255], v[90:91], v[254:255]
	v_pk_add_f32 v[252:253], v[92:93], v[252:253]
	v_pk_add_f32 v[254:255], v[94:95], v[254:255]
	v_cvt_pk_bf16_f32 v116, v80, v81
	v_cvt_pk_bf16_f32 v117, v82, v83
	v_cvt_pk_bf16_f32 v118, v84, v85
	v_cvt_pk_bf16_f32 v119, v86, v87
	v_cvt_pk_bf16_f32 v120, v88, v89
	v_cvt_pk_bf16_f32 v121, v90, v91
	v_cvt_pk_bf16_f32 v122, v92, v93
	v_cvt_pk_bf16_f32 v123, v94, v95
	s_waitcnt lgkmcnt(0)
	v_mfma_f32_32x32x16_bf16 v[48:63], v[212:215], v[116:119], v[48:63]
	v_exp_f32_e32 v64, v64
	v_exp_f32_e32 v65, v65
	v_exp_f32_e32 v66, v66
	v_exp_f32_e32 v67, v67
	v_mfma_f32_32x32x16_bf16 v[32:47], v[216:219], v[116:119], v[32:47]
	v_exp_f32_e32 v68, v68
	v_exp_f32_e32 v69, v69
	v_exp_f32_e32 v70, v70
	v_exp_f32_e32 v71, v71
	v_mfma_f32_32x32x16_bf16 v[48:63], v[220:223], v[120:123], v[48:63]
	v_exp_f32_e32 v72, v72
	v_exp_f32_e32 v73, v73
	v_exp_f32_e32 v74, v74
	v_exp_f32_e32 v75, v75
	v_mfma_f32_32x32x16_bf16 v[32:47], v[224:227], v[120:123], v[32:47]
	v_exp_f32_e32 v76, v76
	v_exp_f32_e32 v77, v77
	v_exp_f32_e32 v78, v78
	v_exp_f32_e32 v79, v79
	v_pk_add_f32 v[252:253], v[64:65], v[252:253]
	v_pk_add_f32 v[254:255], v[66:67], v[254:255]
	v_pk_add_f32 v[252:253], v[68:69], v[252:253]
	v_pk_add_f32 v[254:255], v[70:71], v[254:255]
	v_pk_add_f32 v[252:253], v[72:73], v[252:253]
	v_pk_add_f32 v[254:255], v[74:75], v[254:255]
	v_pk_add_f32 v[252:253], v[76:77], v[252:253]
	v_pk_add_f32 v[254:255], v[78:79], v[254:255]
	v_cvt_pk_bf16_f32 v124, v64, v65
	v_cvt_pk_bf16_f32 v125, v66, v67
	v_cvt_pk_bf16_f32 v126, v68, v69
	v_cvt_pk_bf16_f32 v127, v70, v71
	v_pk_add_f32 v[252:253], v[252:253], v[254:255]
	v_cvt_pk_bf16_f32 v80, v72, v73
	v_cvt_pk_bf16_f32 v81, v74, v75
	v_cvt_pk_bf16_f32 v82, v76, v77
	v_cvt_pk_bf16_f32 v83, v78, v79
	v_add_f32_e32 v252, v252, v253
	v_add_f32_e32 v175, v175, v252
	v_mfma_f32_32x32x16_bf16 v[48:63], v[228:231], v[124:127], v[48:63]
	v_mfma_f32_32x32x16_bf16 v[32:47], v[232:235], v[124:127], v[32:47]
	v_mfma_f32_32x32x16_bf16 v[48:63], v[236:239], v[80:83], v[48:63]
	v_mfma_f32_32x32x16_bf16 v[32:47], v[240:243], v[80:83], v[32:47]

; template <int BR>
; DI void attn_branch(const AttnCtx& c, unsigned long long tmask, const bf16_t* kbase, size_t kpitch, const bf16_t* vbase, size_t vpitch, f32x16 (&o)[2], float& lsum) {
;     ...
;                 f32x16 s0, s1;
; #pragma unroll
;                 for (int i = 0; i < 16; ++i) { s0[i] = sbias; s1[i] = sbias; }
; #pragma unroll
;                 for (int st = 0; st < 4; ++st) {
;                     const bf16x8 kf0 = *(const LAS bf16x8*)(Ks + c.qi * 72 + 16 * st + 8 * c.hi), kf1 = *(const LAS bf16x8*)(Ks + (32 + c.qi) * 72 + 16 * st + 8 * c.hi);
;                     s0 = MFMA32(kf0, c.q[st], s0); s1 = MFMA32(kf1, c.q[st], s1);
;                 }
;                 float p0[16], p1[16];
; #pragma unroll
;                 for (int i = 0; i < 16; ++i) { p0[i] = __builtin_amdgcn_exp2f(s0[i]); p1[i] = __builtin_amdgcn_exp2f(s1[i]); }
;                 {
;                     float l0 = 0.f, l1 = 0.f;
; #pragma unroll
;                     for (int i = 0; i < 16; ++i) { l0 += p0[i]; l1 += p1[i]; }
;                     lsum += l0 + l1;
;                 }
;                 if (BR == 1) {
; #pragma unroll
;                     for (int gq = 0; gq < 4; ++gq) {
;                         const int jj = jc * 16 + gq * 2 + c.hi;
;                         __hip_atomic_fetch_add(c.impw + jj, (p0[4 * gq] + p0[4 * gq + 1]) + (p0[4 * gq + 2] + p0[4 * gq + 3]), __ATOMIC_RELAXED, __HIP_MEMORY_SCOPE_WORKGROUP);
;                         __hip_atomic_fetch_add(c.impw + jj + 1, p0[4 * gq + 3], __ATOMIC_RELAXED, __HIP_MEMORY_SCOPE_WORKGROUP);
;                     }
; #pragma unroll
;                     for (int gq = 0; gq < 4; ++gq) {
;                         const int jj = jc * 16 + 8 + gq * 2 + c.hi;
;                         __hip_atomic_fetch_add(c.impw + jj, (p1[4 * gq] + p1[4 * gq + 1]) + (p1[4 * gq + 2] + p1[4 * gq + 3]), __ATOMIC_RELAXED, __HIP_MEMORY_SCOPE_WORKGROUP);
;                         if (jj + 1 < 64) __hip_atomic_fetch_add(c.impw + jj + 1, p1[4 * gq + 3], __ATOMIC_RELAXED, __HIP_MEMORY_SCOPE_WORKGROUP);
;                     }
;                 }
;                 if (BR != 0) {
;                     unsigned pa[8], pb[8];
; #pragma unroll
;                     for (int i = 0; i < 8; ++i) { pa[i] = pk2(p0[2 * i], p0[2 * i + 1]); pb[i] = pk2(p1[2 * i], p1[2 * i + 1]); }
; #pragma unroll
;                     for (int f = 0; f < 2; ++f) {
.LBB0_403:
	v_lshlrev_b32_e32 v96, 1, v170
	v_add3_u32 v201, s11, v185, v96
	ds_read_b128 v[212:215], v201
	ds_read_b128 v[216:219], v201 offset:4608
	ds_read_b128 v[220:223], v201 offset:32
	ds_read_b128 v[224:227], v201 offset:4640
	ds_read_b128 v[228:231], v201 offset:64
	ds_read_b128 v[232:235], v201 offset:4672
	ds_read_b128 v[236:239], v201 offset:96
	ds_read_b128 v[240:243], v201 offset:4704
	s_waitcnt lgkmcnt(7)
	v_mfma_f32_32x32x16_bf16 v[96:111], v[212:215], v[130:133], 0
	s_waitcnt lgkmcnt(5)
	v_mfma_f32_32x32x16_bf16 v[96:111], v[220:223], v[134:137], v[96:111]
	s_waitcnt lgkmcnt(3)
	v_mfma_f32_32x32x16_bf16 v[96:111], v[228:231], v[138:141], v[96:111]
	s_waitcnt lgkmcnt(1)
	v_mfma_f32_32x32x16_bf16 v[96:111], v[236:239], v[142:145], v[96:111]
	s_waitcnt lgkmcnt(0)
	v_mfma_f32_32x32x16_bf16 v[112:127], v[216:219], v[130:133], 0
	v_mfma_f32_32x32x16_bf16 v[112:127], v[224:227], v[134:137], v[112:127]
	s_nop 9
	v_exp_f32_e32 v96, v96
	v_exp_f32_e32 v97, v97
	v_exp_f32_e32 v98, v98
	v_mfma_f32_32x32x16_bf16 v[112:127], v[232:235], v[138:141], v[112:127]
	v_exp_f32_e32 v99, v99
	v_exp_f32_e32 v100, v100
	v_exp_f32_e32 v101, v101
	v_mfma_f32_32x32x16_bf16 v[112:127], v[240:243], v[142:145], v[112:127]
	v_add3_u32 v251, s11, v186, v170
	v_add_u32_e32 v255, 0x2000, v251
	v_add_u32_e32 v251, 0x3000, v251
	ds_read2_b64 v[212:215], v255 offset0:128 offset1:130
	ds_read2_b64 v[216:219], v251 offset0:160 offset1:162
	ds_read2_b64 v[220:223], v255 offset0:132 offset1:134
	ds_read2_b64 v[224:227], v251 offset0:164 offset1:166
	ds_read2_b64 v[228:231], v255 offset0:136 offset1:138
	ds_read2_b64 v[232:235], v251 offset0:168 offset1:170
	ds_read2_b64 v[236:239], v255 offset0:140 offset1:142
	ds_read2_b64 v[240:243], v251 offset0:172 offset1:174
	v_exp_f32_e32 v102, v102
	v_exp_f32_e32 v103, v103
	v_exp_f32_e32 v104, v104
	v_exp_f32_e32 v105, v105
	v_exp_f32_e32 v106, v106
	v_exp_f32_e32 v107, v107
	v_exp_f32_e32 v108, v108
	v_exp_f32_e32 v109, v109
	v_exp_f32_e32 v110, v110
	v_exp_f32_e32 v111, v111
	v_pk_add_f32 v[252:253], v[96:97], v[98:99]
	v_pk_add_f32 v[254:255], v[100:101], v[102:103]
	v_pk_add_f32 v[252:253], v[104:105], v[252:253]
	v_pk_add_f32 v[254:255], v[106:107], v[254:255]
	v_pk_add_f32 v[252:253], v[108:109], v[252:253]
	v_pk_add_f32 v[254:255], v[110:111], v[254:255]
	v_cvt_pk_bf16_f32 v202, v96, v97
	v_cvt_pk_bf16_f32 v203, v98, v99
	v_cvt_pk_bf16_f32 v204, v100, v101
	v_cvt_pk_bf16_f32 v205, v102, v103
	v_cvt_pk_bf16_f32 v206, v104, v105
	v_cvt_pk_bf16_f32 v207, v106, v107
	v_cvt_pk_bf16_f32 v208, v108, v109
	v_cvt_pk_bf16_f32 v209, v110, v111
	s_waitcnt lgkmcnt(0)
	v_mfma_f32_32x32x16_bf16 v[80:95], v[212:215], v[202:205], v[80:95]
	v_exp_f32_e32 v112, v112
	v_exp_f32_e32 v113, v113
	v_exp_f32_e32 v114, v114
	v_exp_f32_e32 v115, v115
	v_mfma_f32_32x32x16_bf16 v[64:79], v[216:219], v[202:205], v[64:79]
	v_exp_f32_e32 v116, v116
	v_exp_f32_e32 v117, v117
	v_exp_f32_e32 v118, v118
	v_exp_f32_e32 v119, v119
	v_mfma_f32_32x32x16_bf16 v[80:95], v[220:223], v[206:209], v[80:95]
	v_exp_f32_e32 v120, v120
	v_exp_f32_e32 v121, v121
	v_exp_f32_e32 v122, v122
	v_exp_f32_e32 v123, v123
	v_mfma_f32_32x32x16_bf16 v[64:79], v[224:227], v[206:209], v[64:79]
	v_exp_f32_e32 v124, v124
	v_exp_f32_e32 v125, v125
	v_exp_f32_e32 v126, v126
	v_exp_f32_e32 v127, v127
	v_pk_add_f32 v[252:253], v[112:113], v[252:253]
	v_pk_add_f32 v[254:255], v[114:115], v[254:255]
	v_pk_add_f32 v[252:253], v[116:117], v[252:253]
	v_pk_add_f32 v[254:255], v[118:119], v[254:255]
	v_pk_add_f32 v[252:253], v[120:121], v[252:253]
	v_pk_add_f32 v[254:255], v[122:123], v[254:255]
	v_pk_add_f32 v[252:253], v[124:125], v[252:253]
	v_pk_add_f32 v[254:255], v[126:127], v[254:255]
	v_cvt_pk_bf16_f32 v96, v112, v113
	v_cvt_pk_bf16_f32 v97, v114, v115
	v_cvt_pk_bf16_f32 v98, v116, v117
	v_cvt_pk_bf16_f32 v99, v118, v119
	v_pk_add_f32 v[252:253], v[252:253], v[254:255]
	v_cvt_pk_bf16_f32 v100, v120, v121
	v_cvt_pk_bf16_f32 v101, v122, v123
	v_cvt_pk_bf16_f32 v102, v124, v125
	v_cvt_pk_bf16_f32 v103, v126, v127
	v_add_f32_e32 v252, v252, v253
	v_add_f32_e32 v174, v174, v252
	v_mfma_f32_32x32x16_bf16 v[80:95], v[228:231], v[96:99], v[80:95]
	v_mfma_f32_32x32x16_bf16 v[64:79], v[232:235], v[96:99], v[64:79]
	v_mfma_f32_32x32x16_bf16 v[80:95], v[236:239], v[100:103], v[80:95]
	v_mfma_f32_32x32x16_bf16 v[64:79], v[240:243], v[100:103], v[64:79]
	s_or_b64 exec, exec, s[0:1]
	s_andn2_b64 vcc, exec, s[4:5]
	s_xor_b64 s[2:3], s[2:3], -1
	s_cbranch_vccz .LBB0_306
